# pass-1 GLA unit: removed the now-dead V-section address arithmetic (58 instructions per unit) left behind by the V-image load hoist
# speedup vs baseline: 1.0015x; 1.0015x over previous
; #define LAS __attribute__((address_space(3)))
; template <int PASS>
; __device__ __forceinline__ void gla_unit(LAS unsigned char* lds, int ch, int h, const bf16* PROJ, const bf16* GT, bf16* STG, float* DECG, bf16* OMIX, const float* gla_norm) {
;     ...
;         OFFS[(d * 4 + qt) * 64 + kk] = d ? c[0] : c[15];
;         { const int vcol = tid & 127, q4 = tid >> 7; const bf16* vp = PROJ + (m0 + 16 * q4) * LDP + PV + h * 128 + vcol; unsigned vv[16];
; #pragma unroll
;           for (int jj = 0; jj < 16; ++jj) vv[jj] = vp[(size_t)jj * LDP];
; #pragma unroll
;           for (int jj = 0; jj < 16; ++jj) asm volatile("" : "+v"(vv[jj]));
;           v4u w0, w1; w0.x = vv[0] | (vv[1] << 16); w0.y = vv[2] | (vv[3] << 16); w0.z = vv[4] | (vv[5] << 16); w0.w = vv[6] | (vv[7] << 16);
;           w1.x = vv[8] | (vv[9] << 16); w1.y = vv[10] | (vv[11] << 16); w1.z = vv[12] | (vv[13] << 16); w1.w = vv[14] | (vv[15] << 16);
;           *(LAS v4u*)(VT + vcol * RS + q4 * 32) = w0; *(LAS v4u*)(VT + vcol * RS + q4 * 32 + 16) = w1; }
;         __syncthreads();
;         float off = 0.f, tot = 0.f;
; #pragma unroll
;         for (int q2 = 0; q2 < 4; ++q2) { const float t = OFFS[(d * 4 + q2) * 64 + kk]; tot += t; if (d ? (q2 > qt) : (q2 < qt)) off += t; }
.LBB0_764:
	s_or_b64 exec, exec, s[0:1]
	v_ashrrev_i32_e32 v5, 7, v114
	v_and_b32_e32 v3, 0x7f, v114
	v_lshlrev_b32_e32 v115, 2, v113
	v_mul_u32_u24_e32 v3, 0x90, v3
	v_lshlrev_b32_e32 v5, 5, v5
	v_add3_u32 v3, 0, v3, v5
	s_mov_b64 s[0:1], 0
	v_mov_b32_e32 v7, v160
	v_mov_b32_e32 v9, v161
	v_mov_b32_e32 v11, v162
	v_mov_b32_e32 v13, v163
	v_mov_b32_e32 v15, v164
	v_mov_b32_e32 v17, v165
	v_mov_b32_e32 v19, v166
	v_mov_b32_e32 v21, v167
	v_mov_b32_e32 v23, v168
	v_mov_b32_e32 v28, v169
	v_mov_b32_e32 v29, v170
	v_mov_b32_e32 v30, v171
	v_mov_b32_e32 v31, v172
	v_mov_b32_e32 v32, v173
	v_mov_b32_e32 v33, v174
	v_mov_b32_e32 v34, v175
	v_lshlrev_b32_e32 v35, 10, v55
	v_lshlrev_b32_e32 v25, 8, v36
	v_add_u32_e32 v26, s70, v35
	v_cndmask_b32_e32 v24, v83, v18, vcc
	v_add3_u32 v25, v26, v25, v115
	ds_write_b32 v25, v24
	s_waitcnt vmcnt(15)
	s_waitcnt vmcnt(14)
	s_waitcnt vmcnt(13)
	s_waitcnt vmcnt(12)
	s_waitcnt vmcnt(11)
	s_waitcnt vmcnt(10)
	s_waitcnt vmcnt(9)
	s_waitcnt vmcnt(8)
	s_waitcnt vmcnt(7)
	s_waitcnt vmcnt(6)
	s_waitcnt vmcnt(5)
	s_waitcnt vmcnt(4)
	s_waitcnt vmcnt(3)
	v_lshl_or_b32 v24, v9, 16, v7
	v_lshl_or_b32 v25, v13, 16, v11
	v_lshl_or_b32 v26, v17, 16, v15
	v_lshl_or_b32 v27, v21, 16, v19
	s_waitcnt vmcnt(2)
	s_waitcnt vmcnt(1)
	s_waitcnt vmcnt(0)
	v_lshl_or_b32 v28, v28, 16, v23
	v_lshl_or_b32 v29, v30, 16, v29
	v_lshl_or_b32 v30, v32, 16, v31
	v_lshl_or_b32 v31, v34, 16, v33
	ds_write_b128 v3, v[24:27] offset:55296
	ds_write_b128 v3, v[28:31] offset:55312
	v_add_u32_e32 v3, s70, v115
	v_add_u32_e32 v3, v3, v35
	s_waitcnt lgkmcnt(0)
	s_barrier
	ds_read2st64_b32 v[24:25], v3 offset1:1
	v_cmp_eq_u32_e64 s[6:7], 0, v36
	s_and_saveexec_b64 s[8:9], s[4:5]
	s_xor_b64 s[12:13], exec, s[8:9]
	v_cmp_lt_u32_e64 s[8:9], 1, v36
	s_and_b64 s[0:1], s[8:9], exec
	s_or_saveexec_b64 s[8:9], s[12:13]
	s_waitcnt lgkmcnt(0)
	v_add_f32_e32 v5, 0, v24
	s_or_b64 s[12:13], vcc, s[6:7]
	v_cndmask_b32_e64 v7, v5, 0, s[12:13]
	v_mov_b32_e32 v5, v7
	s_xor_b64 exec, exec, s[8:9]
	s_andn2_b64 s[0:1], s[0:1], exec
	s_and_b64 s[6:7], s[6:7], exec
	v_mov_b32_e32 v5, 0
	s_or_b64 s[0:1], s[0:1], s[6:7]
	s_or_b64 exec, exec, s[8:9]
	s_and_saveexec_b64 s[6:7], s[0:1]
	v_add_f32_e32 v5, v25, v7
	s_or_b64 exec, exec, s[6:7]
	ds_read_b32 v7, v3 offset:512
	s_mov_b64 s[0:1], 0
	v_cmp_eq_u32_e64 s[6:7], 3, v36
	s_and_saveexec_b64 s[8:9], s[4:5]
	s_xor_b64 s[4:5], exec, s[8:9]
	s_cbranch_execnz .LBB0_784
	s_andn2_saveexec_b64 s[6:7], s[4:5]
	s_cbranch_execnz .LBB0_785
